# MemKV GEMM tiles of phase 1 use the paired-DMA pipelined K-loop too; W_mem_kv^T stored chunk-swizzled
# baseline (speedup 1.0000x reference)
.Ltr_p_d1:
	s_lshr_b32 s6, s5, 4
	s_and_b32 s7, s5, 15
	s_mov_b32 s12, 0x1000
	s_movk_i32 s13, 31
	s_mul_i32 s8, s6, 0x40000
	s_lshl_b32 s9, s7, 8
	s_add_u32 s8, s8, s9
	s_add_u32 s10, s32, s8
	s_addc_u32 s11, s33, 0
	s_lshl_b32 s8, s7, 18
	s_add_u32 s8, s8, 0x17e88000
	s_add_u32 s14, s94, s8
	s_addc_u32 s15, s95, 0
	s_branch .Ltr_p_end

.LBB0_133:
	v_mov_b32_e32 v8, v204
	s_ashr_i32 s46, s16, 3
	s_and_b32 s33, s31, 7
	v_bfe_u32 v0, v8, 4, 2
	s_ashr_i32 s47, s46, 31
	v_bfe_u32 v2, v8, 2, 4
	v_bitop3_b32 v0, v0, v8, 3 bitop3:0x78
	s_mov_b32 s53, 0x1fffc0
	s_lshl_b32 s52, s33, 19
	s_and_b32 s33, s16, 7
	s_lshl_b64 s[46:47], s[46:47], 20
	v_ashrrev_i32_e32 v1, 6, v8
	v_lshlrev_b32_e32 v9, 3, v0
	v_and_or_b32 v0, v8, s53, v2
	s_add_u32 s48, s17, s46
	v_lshl_or_b32 v0, v0, 11, v9
	v_lshlrev_b32_e32 v3, 16, v1
	v_lshl_add_u32 v133, v1, 12, 32
	v_lshlrev_b32_e32 v1, 11, v1
	s_addc_u32 s49, s22, s47
	v_sub_u32_e32 v134, v133, v1
	v_ashrrev_i32_e32 v1, 31, v0
	v_lshl_add_u64 v[0:1], v[0:1], 1, s[48:49]
	v_readfirstlane_b32 s48, v133
	v_add_u32_e32 v12, 0x400, v133
	s_mov_b32 m0, s48
	v_readfirstlane_b32 s48, v12
	global_load_lds_dwordx4 v[0:1], off
	v_lshl_add_u64 v[6:7], v[0:1], 0, s[6:7]
	s_mov_b32 m0, s48
	s_mov_b64 s[48:49], 0x20000
	v_add_u32_e32 v12, 0x800, v133
	v_lshlrev_b32_e32 v10, 11, v2
	global_load_lds_dwordx4 v[6:7], off
	v_lshl_add_u64 v[6:7], v[0:1], 0, s[48:49]
	v_readfirstlane_b32 s48, v12
	s_lshl_b32 s50, s33, 19
	v_or3_b32 v2, v10, v3, v9
	s_mov_b32 m0, s48
	s_mov_b64 s[48:49], 0x30000
	v_add_u32_e32 v12, 0xc00, v133
	s_add_u32 s50, s23, s50
	v_add_u32_e32 v11, 0x4000, v134
	v_ashrrev_i32_e32 v3, 31, v2
	global_load_lds_dwordx4 v[6:7], off
	v_lshl_add_u64 v[6:7], v[0:1], 0, s[48:49]
	v_readfirstlane_b32 s48, v12
	s_addc_u32 s51, s28, 0
	v_lshlrev_b64 v[2:3], 1, v[2:3]
	v_lshrrev_b32_e32 v240, 4, v10
	v_add_u32_e32 v2, v2, v240
	s_mov_b32 m0, s48
	v_readfirstlane_b32 s48, v11
	v_add_u32_e32 v11, 0x4400, v134
	v_lshl_add_u64 v[4:5], s[50:51], 0, v[2:3]
	global_load_lds_dwordx4 v[6:7], off
	s_mov_b32 m0, s48
	v_readfirstlane_b32 s48, v11
	v_add_u32_e32 v11, 0x6000, v133
	global_load_lds_dwordx4 v[4:5], off
	s_mov_b64 s[38:39], 0x10800
	v_lshl_add_u64 v[6:7], v[4:5], 0, s[38:39]
	s_mov_b32 m0, s48
	v_readfirstlane_b32 s48, v11
	v_add_u32_e32 v11, 0x6400, v133
	global_load_lds_dwordx4 v[6:7], off
	v_lshl_add_u64 v[6:7], v[0:1], 0, 64
	s_mov_b32 m0, s48
	v_readfirstlane_b32 s48, v11
	global_load_lds_dwordx4 v[6:7], off
	v_lshl_add_u64 v[6:7], v[0:1], 0, s[8:9]
	s_mov_b32 m0, s48
	s_mov_b64 s[48:49], 0x20040
	v_add_u32_e32 v11, 0x6800, v133
	global_load_lds_dwordx4 v[6:7], off
	v_lshl_add_u64 v[6:7], v[0:1], 0, s[48:49]
	v_readfirstlane_b32 s48, v11
	s_mov_b32 m0, s48
	s_mov_b64 s[48:49], 0x30040
	global_load_lds_dwordx4 v[6:7], off
	v_add_u32_e32 v6, 0x6c00, v133
	v_lshl_add_u64 v[0:1], v[0:1], 0, s[48:49]
	v_readfirstlane_b32 s48, v6
	v_add_u32_e32 v6, 0xa000, v134
	s_mov_b32 m0, s48
	v_readfirstlane_b32 s48, v6
	global_load_lds_dwordx4 v[0:1], off
	v_lshl_add_u64 v[0:1], v[4:5], 0, 64
	s_mov_b32 m0, s48
	s_mov_b32 s50, 0
	global_load_lds_dwordx4 v[0:1], off
	s_mov_b64 s[38:39], 0x10840
	v_lshl_add_u64 v[0:1], v[4:5], 0, s[38:39]
	v_add_u32_e32 v4, 0xa400, v134
	v_lshlrev_b32_e32 v5, 6, v8
	v_readfirstlane_b32 s48, v4
	s_mov_b32 m0, s48
	v_bfe_u32 v4, v8, 2, 2
	global_load_lds_dwordx4 v[0:1], off
	v_bfe_u32 v0, v8, 5, 1
	v_lshrrev_b32_e32 v1, 2, v8
	v_bitop3_b32 v1, v0, v1, 3 bitop3:0x78
	v_bitop3_b32 v0, v0, v4, 2 bitop3:0x36
	v_lshlrev_b32_e32 v132, 4, v0
	s_add_u32 s48, s94, s52
	v_lshlrev_b32_e32 v0, 11, v8
	s_addc_u32 s49, s95, 0
	v_and_b32_e32 v0, 0xfffe0000, v0
	v_lshl_add_u64 v[128:129], s[48:49], 0, v[2:3]
	v_or3_b32 v0, v0, v10, v9
	s_add_u32 s48, s94, s46
	v_lshlrev_b32_e32 v135, 4, v1
	v_ashrrev_i32_e32 v1, 31, v0
	s_addc_u32 s49, s95, s47
	v_lshl_add_u64 v[130:131], v[0:1], 1, s[48:49]
	v_mov_b32_e32 v0, 0
	v_and_b32_e32 v136, 0xffffe7c0, v5
	v_and_b32_e32 v137, 0x17c0, v5
	s_mov_b64 s[48:49], 0
	v_mov_b32_e32 v1, v0
	v_mov_b32_e32 v2, v0
	v_mov_b32_e32 v3, v0
	v_mov_b32_e32 v4, v0
	v_mov_b32_e32 v5, v0
	v_mov_b32_e32 v6, v0
	v_mov_b32_e32 v7, v0
	v_mov_b32_e32 v8, v0
	v_mov_b32_e32 v9, v0
	v_mov_b32_e32 v10, v0
	v_mov_b32_e32 v11, v0
	v_mov_b32_e32 v12, v0
	v_mov_b32_e32 v13, v0
	v_mov_b32_e32 v14, v0
	v_mov_b32_e32 v15, v0
	v_mov_b32_e32 v16, v0
	v_mov_b32_e32 v17, v0
	v_mov_b32_e32 v18, v0
	v_mov_b32_e32 v19, v0
	v_mov_b32_e32 v20, v0
	v_mov_b32_e32 v21, v0
	v_mov_b32_e32 v22, v0
	v_mov_b32_e32 v23, v0
	v_mov_b32_e32 v24, v0
	v_mov_b32_e32 v25, v0
	v_mov_b32_e32 v26, v0
	v_mov_b32_e32 v27, v0
	v_mov_b32_e32 v28, v0
	v_mov_b32_e32 v29, v0
	v_mov_b32_e32 v30, v0
	v_mov_b32_e32 v31, v0
	v_mov_b32_e32 v32, v0
	v_mov_b32_e32 v33, v0
	v_mov_b32_e32 v34, v0
	v_mov_b32_e32 v35, v0
	v_mov_b32_e32 v36, v0
	v_mov_b32_e32 v37, v0
	v_mov_b32_e32 v38, v0
	v_mov_b32_e32 v39, v0
	v_mov_b32_e32 v40, v0
	v_mov_b32_e32 v41, v0
	v_mov_b32_e32 v42, v0
	v_mov_b32_e32 v43, v0
	v_mov_b32_e32 v44, v0
	v_mov_b32_e32 v45, v0
	v_mov_b32_e32 v46, v0
	v_mov_b32_e32 v47, v0
	v_mov_b32_e32 v48, v0
	v_mov_b32_e32 v49, v0
	v_mov_b32_e32 v50, v0
	v_mov_b32_e32 v51, v0
	v_mov_b32_e32 v52, v0
	v_mov_b32_e32 v53, v0
	v_mov_b32_e32 v54, v0
	v_mov_b32_e32 v55, v0
	v_mov_b32_e32 v56, v0
	v_mov_b32_e32 v57, v0
	v_mov_b32_e32 v58, v0
	v_mov_b32_e32 v59, v0
	v_mov_b32_e32 v60, v0
	v_mov_b32_e32 v61, v0
	v_mov_b32_e32 v62, v0
	v_mov_b32_e32 v63, v0
	v_mov_b32_e32 v64, v0
	v_mov_b32_e32 v65, v0
	v_mov_b32_e32 v66, v0
	v_mov_b32_e32 v67, v0
	v_mov_b32_e32 v68, v0
	v_mov_b32_e32 v69, v0
	v_mov_b32_e32 v70, v0
	v_mov_b32_e32 v71, v0
	v_mov_b32_e32 v72, v0
	v_mov_b32_e32 v73, v0
	v_mov_b32_e32 v74, v0
	v_mov_b32_e32 v75, v0
	v_mov_b32_e32 v76, v0
	v_mov_b32_e32 v77, v0
	v_mov_b32_e32 v78, v0
	v_mov_b32_e32 v79, v0
	v_mov_b32_e32 v80, v0
	v_mov_b32_e32 v81, v0
	v_mov_b32_e32 v82, v0
	v_mov_b32_e32 v83, v0
	v_mov_b32_e32 v84, v0
	v_mov_b32_e32 v85, v0
	v_mov_b32_e32 v86, v0
	v_mov_b32_e32 v87, v0
	v_mov_b32_e32 v88, v0
	v_mov_b32_e32 v89, v0
	v_mov_b32_e32 v90, v0
	v_mov_b32_e32 v91, v0
	v_mov_b32_e32 v92, v0
	v_mov_b32_e32 v93, v0
	v_mov_b32_e32 v94, v0
	v_mov_b32_e32 v95, v0
	v_mov_b32_e32 v96, v0
	v_mov_b32_e32 v97, v0
	v_mov_b32_e32 v98, v0
	v_mov_b32_e32 v99, v0
	v_mov_b32_e32 v100, v0
	v_mov_b32_e32 v101, v0
	v_mov_b32_e32 v102, v0
	v_mov_b32_e32 v103, v0
	v_mov_b32_e32 v104, v0
	v_mov_b32_e32 v105, v0
	v_mov_b32_e32 v106, v0
	v_mov_b32_e32 v107, v0
	v_mov_b32_e32 v108, v0
	v_mov_b32_e32 v109, v0
	v_mov_b32_e32 v110, v0
	v_mov_b32_e32 v111, v0
	v_mov_b32_e32 v112, v0
	v_mov_b32_e32 v113, v0
	v_mov_b32_e32 v114, v0
	v_mov_b32_e32 v115, v0
	v_mov_b32_e32 v116, v0
	v_mov_b32_e32 v117, v0
	v_mov_b32_e32 v118, v0
	v_mov_b32_e32 v119, v0
	v_mov_b32_e32 v120, v0
	v_mov_b32_e32 v121, v0
	v_mov_b32_e32 v122, v0
	v_mov_b32_e32 v123, v0
	v_mov_b32_e32 v124, v0
	v_mov_b32_e32 v125, v0
	v_mov_b32_e32 v126, v0
	v_mov_b32_e32 v127, v0
	v_add3_u32 v230, v136, v135, 32
	v_add3_u32 v231, v136, v132, 32
	v_add_u32_e32 v232, 0x4020, v137
	v_add_u32_e32 v233, v232, v132
	v_add_u32_e32 v232, v232, v135
	v_subrev_u32_e32 v234, s94, v130
	v_subrev_u32_e32 v238, s94, v128
	v_add_u32_e32 v234, 0x19a88080, v234
	v_sub_u32_e32 v238, v238, v240
	v_add_u32_e32 v238, 0x17e88000, v238
	v_add_u32_e32 v235, 0x10000, v234
	v_add_u32_e32 v236, 0x20000, v234
	v_add_u32_e32 v237, 0x30000, v234
	v_add_u32_e32 v239, 0x10000, v238
	v_readfirstlane_b32 s101, v133
	v_readfirstlane_b32 s49, v134
	s_mov_b64 s[98:99], s[94:95]
	s_add_u32 s44, s94, 64
	s_addc_u32 s45, s95, 0
	s_add_u32 s49, s49, 0x4000
	s_movk_i32 s36, 0x80
	s_movk_i32 s37, 0x880
	s_waitcnt vmcnt(6)
	s_barrier
	ds_read_b128 v[170:173], v232 offset:0
	ds_read_b128 v[174:177], v232 offset:2048
	ds_read_b128 v[178:181], v230 offset:0
	ds_read_b128 v[182:185], v230 offset:2048
	ds_read_b128 v[186:189], v230 offset:4096
	ds_read_b128 v[190:193], v230 offset:6144
	s_waitcnt lgkmcnt(2)
	s_setprio 1
	v_mfma_f32_32x32x16_bf16 v[112:127], v[178:181], v[170:173], v[112:127]
	v_mfma_f32_32x32x16_bf16 v[96:111], v[178:181], v[174:177], v[96:111]
	v_mfma_f32_32x32x16_bf16 v[80:95], v[182:185], v[170:173], v[80:95]
	v_mfma_f32_32x32x16_bf16 v[64:79], v[182:185], v[174:177], v[64:79]
	s_setprio 0
	ds_read_b128 v[206:209], v233 offset:0
	ds_read_b128 v[210:213], v233 offset:2048
	ds_read_b128 v[214:217], v231 offset:0
	ds_read_b128 v[218:221], v231 offset:2048
	s_waitcnt lgkmcnt(4)
	s_setprio 1
	v_mfma_f32_32x32x16_bf16 v[48:63], v[186:189], v[170:173], v[48:63]
	v_mfma_f32_32x32x16_bf16 v[32:47], v[186:189], v[174:177], v[32:47]
	v_mfma_f32_32x32x16_bf16 v[16:31], v[190:193], v[170:173], v[16:31]
	v_mfma_f32_32x32x16_bf16 v[0:15], v[190:193], v[174:177], v[0:15]
	s_setprio 0
	ds_read_b128 v[222:225], v231 offset:4096
	ds_read_b128 v[226:229], v231 offset:6144
	s_waitcnt lgkmcnt(2)
	s_setprio 1
	v_mfma_f32_32x32x16_bf16 v[112:127], v[214:217], v[206:209], v[112:127]
	v_mfma_f32_32x32x16_bf16 v[96:111], v[214:217], v[210:213], v[96:111]
	v_mfma_f32_32x32x16_bf16 v[80:95], v[218:221], v[206:209], v[80:95]
	v_mfma_f32_32x32x16_bf16 v[64:79], v[218:221], v[210:213], v[64:79]
	s_setprio 0
	s_mov_b32 s100, 10
.Lp1k_kloop:
	s_waitcnt vmcnt(0) lgkmcnt(0)
	s_barrier
	ds_read_b128 v[170:173], v232 offset:24576
	ds_read_b128 v[174:177], v232 offset:26624
	ds_read_b128 v[178:181], v230 offset:24576
	ds_read_b128 v[182:185], v230 offset:26624
	ds_read_b128 v[186:189], v230 offset:28672
	ds_read_b128 v[190:193], v230 offset:30720
	s_setprio 1
	v_mfma_f32_32x32x16_bf16 v[48:63], v[222:225], v[206:209], v[48:63]
	v_mfma_f32_32x32x16_bf16 v[32:47], v[222:225], v[210:213], v[32:47]
	v_mfma_f32_32x32x16_bf16 v[16:31], v[226:229], v[206:209], v[16:31]
	v_mfma_f32_32x32x16_bf16 v[0:15], v[226:229], v[210:213], v[0:15]
	s_setprio 0
	s_add_u32 m0, s101, 0xc000
	s_nop 0
	global_load_lds_dwordx4 v234, s[98:99]
	s_add_u32 m0, s101, 0x0
	s_nop 0
	global_load_lds_dwordx4 v234, s[44:45]
	s_add_u32 m0, s101, 0xc400
	s_nop 0
	global_load_lds_dwordx4 v235, s[98:99]
	s_add_u32 m0, s101, 0x400
	s_nop 0
	global_load_lds_dwordx4 v235, s[44:45]
	s_waitcnt lgkmcnt(2)
	s_setprio 1
	v_mfma_f32_32x32x16_bf16 v[112:127], v[178:181], v[170:173], v[112:127]
	v_mfma_f32_32x32x16_bf16 v[96:111], v[178:181], v[174:177], v[96:111]
	v_mfma_f32_32x32x16_bf16 v[80:95], v[182:185], v[170:173], v[80:95]
	v_mfma_f32_32x32x16_bf16 v[64:79], v[182:185], v[174:177], v[64:79]
	s_setprio 0
	ds_read_b128 v[206:209], v233 offset:24576
	ds_read_b128 v[210:213], v233 offset:26624
	ds_read_b128 v[214:217], v231 offset:24576
	ds_read_b128 v[218:221], v231 offset:26624
	s_add_u32 m0, s101, 0xc800
	s_nop 0
	global_load_lds_dwordx4 v236, s[98:99]
	s_add_u32 m0, s101, 0x800
	s_nop 0
	global_load_lds_dwordx4 v236, s[44:45]
	s_add_u32 m0, s101, 0xcc00
	s_nop 0
	global_load_lds_dwordx4 v237, s[98:99]
	s_add_u32 m0, s101, 0xc00
	s_nop 0
	global_load_lds_dwordx4 v237, s[44:45]
	s_waitcnt lgkmcnt(4)
	s_setprio 1
	v_mfma_f32_32x32x16_bf16 v[48:63], v[186:189], v[170:173], v[48:63]
	v_mfma_f32_32x32x16_bf16 v[32:47], v[186:189], v[174:177], v[32:47]
	v_mfma_f32_32x32x16_bf16 v[16:31], v[190:193], v[170:173], v[16:31]
	v_mfma_f32_32x32x16_bf16 v[0:15], v[190:193], v[174:177], v[0:15]
	s_setprio 0
	ds_read_b128 v[222:225], v231 offset:28672
	ds_read_b128 v[226:229], v231 offset:30720
	v_xad_u32 v241, s36, v240, v238
	v_xad_u32 v242, s37, v240, v239
	s_add_u32 m0, s49, 0xc000
	s_nop 0
	global_load_lds_dwordx4 v241, s[94:95]
	s_add_u32 m0, s49, 0xffffffc0
	s_nop 0
	global_load_lds_dwordx4 v241, s[94:95] offset:64
	s_add_u32 m0, s49, 0xc400
	s_nop 0
	global_load_lds_dwordx4 v242, s[94:95]
	s_add_u32 m0, s49, 0x3c0
	s_nop 0
	global_load_lds_dwordx4 v242, s[94:95] offset:64
	s_add_u32 s36, s36, 0x80
	s_xor_b32 s37, s36, 0x800
	s_add_u32 s98, s98, 128
	s_addc_u32 s99, s99, 0
	s_add_u32 s44, s44, 128
	s_addc_u32 s45, s45, 0
	s_waitcnt lgkmcnt(2)
	s_setprio 1
	v_mfma_f32_32x32x16_bf16 v[112:127], v[214:217], v[206:209], v[112:127]
	v_mfma_f32_32x32x16_bf16 v[96:111], v[214:217], v[210:213], v[96:111]
	v_mfma_f32_32x32x16_bf16 v[80:95], v[218:221], v[206:209], v[80:95]
	v_mfma_f32_32x32x16_bf16 v[64:79], v[218:221], v[210:213], v[64:79]
	s_setprio 0
	s_waitcnt vmcnt(0) lgkmcnt(0)
	s_barrier
	ds_read_b128 v[170:173], v232 offset:49152
	ds_read_b128 v[174:177], v232 offset:51200
	ds_read_b128 v[178:181], v230 offset:49152
	ds_read_b128 v[182:185], v230 offset:51200
	ds_read_b128 v[186:189], v230 offset:53248
	ds_read_b128 v[190:193], v230 offset:55296
	s_setprio 1
	v_mfma_f32_32x32x16_bf16 v[48:63], v[222:225], v[206:209], v[48:63]
	v_mfma_f32_32x32x16_bf16 v[32:47], v[222:225], v[210:213], v[32:47]
	v_mfma_f32_32x32x16_bf16 v[16:31], v[226:229], v[206:209], v[16:31]
	v_mfma_f32_32x32x16_bf16 v[0:15], v[226:229], v[210:213], v[0:15]
	s_setprio 0
	s_waitcnt lgkmcnt(2)
	s_setprio 1
	v_mfma_f32_32x32x16_bf16 v[112:127], v[178:181], v[170:173], v[112:127]
	v_mfma_f32_32x32x16_bf16 v[96:111], v[178:181], v[174:177], v[96:111]
	v_mfma_f32_32x32x16_bf16 v[80:95], v[182:185], v[170:173], v[80:95]
	v_mfma_f32_32x32x16_bf16 v[64:79], v[182:185], v[174:177], v[64:79]
	s_setprio 0
	ds_read_b128 v[206:209], v233 offset:49152
	ds_read_b128 v[210:213], v233 offset:51200
	ds_read_b128 v[214:217], v231 offset:49152
	ds_read_b128 v[218:221], v231 offset:51200
	s_waitcnt lgkmcnt(4)
	s_setprio 1
	v_mfma_f32_32x32x16_bf16 v[48:63], v[186:189], v[170:173], v[48:63]
	v_mfma_f32_32x32x16_bf16 v[32:47], v[186:189], v[174:177], v[32:47]
	v_mfma_f32_32x32x16_bf16 v[16:31], v[190:193], v[170:173], v[16:31]
	v_mfma_f32_32x32x16_bf16 v[0:15], v[190:193], v[174:177], v[0:15]
	s_setprio 0
	ds_read_b128 v[222:225], v231 offset:53248
	ds_read_b128 v[226:229], v231 offset:55296
	s_waitcnt lgkmcnt(2)
	s_setprio 1
	v_mfma_f32_32x32x16_bf16 v[112:127], v[214:217], v[206:209], v[112:127]
	v_mfma_f32_32x32x16_bf16 v[96:111], v[214:217], v[210:213], v[96:111]
	v_mfma_f32_32x32x16_bf16 v[80:95], v[218:221], v[206:209], v[80:95]
	v_mfma_f32_32x32x16_bf16 v[64:79], v[218:221], v[210:213], v[64:79]
	s_setprio 0
	s_waitcnt vmcnt(0) lgkmcnt(0)
	s_barrier
	ds_read_b128 v[170:173], v232 offset:0
	ds_read_b128 v[174:177], v232 offset:2048
	ds_read_b128 v[178:181], v230 offset:0
	ds_read_b128 v[182:185], v230 offset:2048
	ds_read_b128 v[186:189], v230 offset:4096
	ds_read_b128 v[190:193], v230 offset:6144
	s_setprio 1
	v_mfma_f32_32x32x16_bf16 v[48:63], v[222:225], v[206:209], v[48:63]
	v_mfma_f32_32x32x16_bf16 v[32:47], v[222:225], v[210:213], v[32:47]
	v_mfma_f32_32x32x16_bf16 v[16:31], v[226:229], v[206:209], v[16:31]
	v_mfma_f32_32x32x16_bf16 v[0:15], v[226:229], v[210:213], v[0:15]
	s_setprio 0
	s_add_u32 m0, s101, 0x6000
	s_nop 0
	global_load_lds_dwordx4 v234, s[98:99]
	s_add_u32 m0, s101, 0xc000
	s_nop 0
	global_load_lds_dwordx4 v234, s[44:45]
	s_add_u32 m0, s101, 0x6400
	s_nop 0
	global_load_lds_dwordx4 v235, s[98:99]
	s_add_u32 m0, s101, 0xc400
	s_nop 0
	global_load_lds_dwordx4 v235, s[44:45]
	s_waitcnt lgkmcnt(2)
	s_setprio 1
	v_mfma_f32_32x32x16_bf16 v[112:127], v[178:181], v[170:173], v[112:127]
	v_mfma_f32_32x32x16_bf16 v[96:111], v[178:181], v[174:177], v[96:111]
	v_mfma_f32_32x32x16_bf16 v[80:95], v[182:185], v[170:173], v[80:95]
	v_mfma_f32_32x32x16_bf16 v[64:79], v[182:185], v[174:177], v[64:79]
	s_setprio 0
	ds_read_b128 v[206:209], v233 offset:0
	ds_read_b128 v[210:213], v233 offset:2048
	ds_read_b128 v[214:217], v231 offset:0
	ds_read_b128 v[218:221], v231 offset:2048
	s_add_u32 m0, s101, 0x6800
	s_nop 0
	global_load_lds_dwordx4 v236, s[98:99]
	s_add_u32 m0, s101, 0xc800
	s_nop 0
	global_load_lds_dwordx4 v236, s[44:45]
	s_add_u32 m0, s101, 0x6c00
	s_nop 0
	global_load_lds_dwordx4 v237, s[98:99]
	s_add_u32 m0, s101, 0xcc00
	s_nop 0
	global_load_lds_dwordx4 v237, s[44:45]
	s_waitcnt lgkmcnt(4)
	s_setprio 1
	v_mfma_f32_32x32x16_bf16 v[48:63], v[186:189], v[170:173], v[48:63]
	v_mfma_f32_32x32x16_bf16 v[32:47], v[186:189], v[174:177], v[32:47]
	v_mfma_f32_32x32x16_bf16 v[16:31], v[190:193], v[170:173], v[16:31]
	v_mfma_f32_32x32x16_bf16 v[0:15], v[190:193], v[174:177], v[0:15]
	s_setprio 0
	ds_read_b128 v[222:225], v231 offset:4096
	ds_read_b128 v[226:229], v231 offset:6144
	v_xad_u32 v241, s36, v240, v238
	v_xad_u32 v242, s37, v240, v239
	s_add_u32 m0, s49, 0x6000
	s_nop 0
	global_load_lds_dwordx4 v241, s[94:95]
	s_add_u32 m0, s49, 0xbfc0
	s_nop 0
	global_load_lds_dwordx4 v241, s[94:95] offset:64
	s_add_u32 m0, s49, 0x6400
	s_nop 0
	global_load_lds_dwordx4 v242, s[94:95]
	s_add_u32 m0, s49, 0xc3c0
	s_nop 0
	global_load_lds_dwordx4 v242, s[94:95] offset:64
	s_add_u32 s36, s36, 0x80
	s_xor_b32 s37, s36, 0x800
	s_add_u32 s98, s98, 128
	s_addc_u32 s99, s99, 0
	s_add_u32 s44, s44, 128
	s_addc_u32 s45, s45, 0
	s_waitcnt lgkmcnt(2)
	s_setprio 1
	v_mfma_f32_32x32x16_bf16 v[112:127], v[214:217], v[206:209], v[112:127]
	v_mfma_f32_32x32x16_bf16 v[96:111], v[214:217], v[210:213], v[96:111]
	v_mfma_f32_32x32x16_bf16 v[80:95], v[218:221], v[206:209], v[80:95]
	v_mfma_f32_32x32x16_bf16 v[64:79], v[218:221], v[210:213], v[64:79]
	s_setprio 0
	s_waitcnt vmcnt(0) lgkmcnt(0)
	s_barrier
	ds_read_b128 v[170:173], v232 offset:24576
	ds_read_b128 v[174:177], v232 offset:26624
	ds_read_b128 v[178:181], v230 offset:24576
	ds_read_b128 v[182:185], v230 offset:26624
	ds_read_b128 v[186:189], v230 offset:28672
	ds_read_b128 v[190:193], v230 offset:30720
	s_setprio 1
	v_mfma_f32_32x32x16_bf16 v[48:63], v[222:225], v[206:209], v[48:63]
	v_mfma_f32_32x32x16_bf16 v[32:47], v[222:225], v[210:213], v[32:47]
	v_mfma_f32_32x32x16_bf16 v[16:31], v[226:229], v[206:209], v[16:31]
	v_mfma_f32_32x32x16_bf16 v[0:15], v[226:229], v[210:213], v[0:15]
	s_setprio 0
	s_waitcnt lgkmcnt(2)
	s_setprio 1
	v_mfma_f32_32x32x16_bf16 v[112:127], v[178:181], v[170:173], v[112:127]
	v_mfma_f32_32x32x16_bf16 v[96:111], v[178:181], v[174:177], v[96:111]
	v_mfma_f32_32x32x16_bf16 v[80:95], v[182:185], v[170:173], v[80:95]
	v_mfma_f32_32x32x16_bf16 v[64:79], v[182:185], v[174:177], v[64:79]
	s_setprio 0
	ds_read_b128 v[206:209], v233 offset:24576
	ds_read_b128 v[210:213], v233 offset:26624
	ds_read_b128 v[214:217], v231 offset:24576
	ds_read_b128 v[218:221], v231 offset:26624
	s_waitcnt lgkmcnt(4)
	s_setprio 1
	v_mfma_f32_32x32x16_bf16 v[48:63], v[186:189], v[170:173], v[48:63]
	v_mfma_f32_32x32x16_bf16 v[32:47], v[186:189], v[174:177], v[32:47]
	v_mfma_f32_32x32x16_bf16 v[16:31], v[190:193], v[170:173], v[16:31]
	v_mfma_f32_32x32x16_bf16 v[0:15], v[190:193], v[174:177], v[0:15]
	s_setprio 0
	ds_read_b128 v[222:225], v231 offset:28672
	ds_read_b128 v[226:229], v231 offset:30720
	s_waitcnt lgkmcnt(2)
	s_setprio 1
	v_mfma_f32_32x32x16_bf16 v[112:127], v[214:217], v[206:209], v[112:127]
	v_mfma_f32_32x32x16_bf16 v[96:111], v[214:217], v[210:213], v[96:111]
	v_mfma_f32_32x32x16_bf16 v[80:95], v[218:221], v[206:209], v[80:95]
	v_mfma_f32_32x32x16_bf16 v[64:79], v[218:221], v[210:213], v[64:79]
	s_setprio 0
	s_waitcnt vmcnt(0) lgkmcnt(0)
	s_barrier
	ds_read_b128 v[170:173], v232 offset:49152
	ds_read_b128 v[174:177], v232 offset:51200
	ds_read_b128 v[178:181], v230 offset:49152
	ds_read_b128 v[182:185], v230 offset:51200
	ds_read_b128 v[186:189], v230 offset:53248
	ds_read_b128 v[190:193], v230 offset:55296
	s_setprio 1
	v_mfma_f32_32x32x16_bf16 v[48:63], v[222:225], v[206:209], v[48:63]
	v_mfma_f32_32x32x16_bf16 v[32:47], v[222:225], v[210:213], v[32:47]
	v_mfma_f32_32x32x16_bf16 v[16:31], v[226:229], v[206:209], v[16:31]
	v_mfma_f32_32x32x16_bf16 v[0:15], v[226:229], v[210:213], v[0:15]
	s_setprio 0
	s_add_u32 m0, s101, 0x0
	s_nop 0
	global_load_lds_dwordx4 v234, s[98:99]
	s_add_u32 m0, s101, 0x6000
	s_nop 0
	global_load_lds_dwordx4 v234, s[44:45]
	s_add_u32 m0, s101, 0x400
	s_nop 0
	global_load_lds_dwordx4 v235, s[98:99]
	s_add_u32 m0, s101, 0x6400
	s_nop 0
	global_load_lds_dwordx4 v235, s[44:45]
	s_waitcnt lgkmcnt(2)
	s_setprio 1
	v_mfma_f32_32x32x16_bf16 v[112:127], v[178:181], v[170:173], v[112:127]
	v_mfma_f32_32x32x16_bf16 v[96:111], v[178:181], v[174:177], v[96:111]
	v_mfma_f32_32x32x16_bf16 v[80:95], v[182:185], v[170:173], v[80:95]
	v_mfma_f32_32x32x16_bf16 v[64:79], v[182:185], v[174:177], v[64:79]
	s_setprio 0
	ds_read_b128 v[206:209], v233 offset:49152
	ds_read_b128 v[210:213], v233 offset:51200
	ds_read_b128 v[214:217], v231 offset:49152
	ds_read_b128 v[218:221], v231 offset:51200
	s_add_u32 m0, s101, 0x800
	s_nop 0
	global_load_lds_dwordx4 v236, s[98:99]
	s_add_u32 m0, s101, 0x6800
	s_nop 0
	global_load_lds_dwordx4 v236, s[44:45]
	s_add_u32 m0, s101, 0xc00
	s_nop 0
	global_load_lds_dwordx4 v237, s[98:99]
	s_add_u32 m0, s101, 0x6c00
	s_nop 0
	global_load_lds_dwordx4 v237, s[44:45]
	s_waitcnt lgkmcnt(4)
	s_setprio 1
	v_mfma_f32_32x32x16_bf16 v[48:63], v[186:189], v[170:173], v[48:63]
	v_mfma_f32_32x32x16_bf16 v[32:47], v[186:189], v[174:177], v[32:47]
	v_mfma_f32_32x32x16_bf16 v[16:31], v[190:193], v[170:173], v[16:31]
	v_mfma_f32_32x32x16_bf16 v[0:15], v[190:193], v[174:177], v[0:15]
	s_setprio 0
	ds_read_b128 v[222:225], v231 offset:53248
	ds_read_b128 v[226:229], v231 offset:55296
	v_xad_u32 v241, s36, v240, v238
	v_xad_u32 v242, s37, v240, v239
	s_add_u32 m0, s49, 0x0
	s_nop 0
	global_load_lds_dwordx4 v241, s[94:95]
	s_add_u32 m0, s49, 0x5fc0
	s_nop 0
	global_load_lds_dwordx4 v241, s[94:95] offset:64
	s_add_u32 m0, s49, 0x400
	s_nop 0
	global_load_lds_dwordx4 v242, s[94:95]
	s_add_u32 m0, s49, 0x63c0
	s_nop 0
	global_load_lds_dwordx4 v242, s[94:95] offset:64
	s_add_u32 s36, s36, 0x80
	s_xor_b32 s37, s36, 0x800
	s_add_u32 s98, s98, 128
	s_addc_u32 s99, s99, 0
	s_add_u32 s44, s44, 128
	s_addc_u32 s45, s45, 0
	s_waitcnt lgkmcnt(2)
	s_setprio 1
	v_mfma_f32_32x32x16_bf16 v[112:127], v[214:217], v[206:209], v[112:127]
	v_mfma_f32_32x32x16_bf16 v[96:111], v[214:217], v[210:213], v[96:111]
	v_mfma_f32_32x32x16_bf16 v[80:95], v[218:221], v[206:209], v[80:95]
	v_mfma_f32_32x32x16_bf16 v[64:79], v[218:221], v[210:213], v[64:79]
	s_setprio 0
	s_waitcnt vmcnt(0) lgkmcnt(0)
	s_barrier
	ds_read_b128 v[170:173], v232 offset:0
	ds_read_b128 v[174:177], v232 offset:2048
	ds_read_b128 v[178:181], v230 offset:0
	ds_read_b128 v[182:185], v230 offset:2048
	ds_read_b128 v[186:189], v230 offset:4096
	ds_read_b128 v[190:193], v230 offset:6144
	s_setprio 1
	v_mfma_f32_32x32x16_bf16 v[48:63], v[222:225], v[206:209], v[48:63]
	v_mfma_f32_32x32x16_bf16 v[32:47], v[222:225], v[210:213], v[32:47]
	v_mfma_f32_32x32x16_bf16 v[16:31], v[226:229], v[206:209], v[16:31]
	v_mfma_f32_32x32x16_bf16 v[0:15], v[226:229], v[210:213], v[0:15]
	s_setprio 0
	s_waitcnt lgkmcnt(2)
	s_setprio 1
	v_mfma_f32_32x32x16_bf16 v[112:127], v[178:181], v[170:173], v[112:127]
	v_mfma_f32_32x32x16_bf16 v[96:111], v[178:181], v[174:177], v[96:111]
	v_mfma_f32_32x32x16_bf16 v[80:95], v[182:185], v[170:173], v[80:95]
	v_mfma_f32_32x32x16_bf16 v[64:79], v[182:185], v[174:177], v[64:79]
	s_setprio 0
	ds_read_b128 v[206:209], v233 offset:0
	ds_read_b128 v[210:213], v233 offset:2048
	ds_read_b128 v[214:217], v231 offset:0
	ds_read_b128 v[218:221], v231 offset:2048
	s_waitcnt lgkmcnt(4)
	s_setprio 1
	v_mfma_f32_32x32x16_bf16 v[48:63], v[186:189], v[170:173], v[48:63]
	v_mfma_f32_32x32x16_bf16 v[32:47], v[186:189], v[174:177], v[32:47]
	v_mfma_f32_32x32x16_bf16 v[16:31], v[190:193], v[170:173], v[16:31]
	v_mfma_f32_32x32x16_bf16 v[0:15], v[190:193], v[174:177], v[0:15]
	s_setprio 0
	ds_read_b128 v[222:225], v231 offset:4096
	ds_read_b128 v[226:229], v231 offset:6144
	s_waitcnt lgkmcnt(2)
	s_setprio 1
	v_mfma_f32_32x32x16_bf16 v[112:127], v[214:217], v[206:209], v[112:127]
	v_mfma_f32_32x32x16_bf16 v[96:111], v[214:217], v[210:213], v[96:111]
	v_mfma_f32_32x32x16_bf16 v[80:95], v[218:221], v[206:209], v[80:95]
	v_mfma_f32_32x32x16_bf16 v[64:79], v[218:221], v[210:213], v[64:79]
	s_setprio 0
	s_sub_u32 s100, s100, 1
	s_cmp_lg_u32 s100, 0
	s_cbranch_scc1 .Lp1k_kloop
	s_waitcnt vmcnt(0) lgkmcnt(0)
	s_barrier
	ds_read_b128 v[170:173], v232 offset:24576
	ds_read_b128 v[174:177], v232 offset:26624
	ds_read_b128 v[178:181], v230 offset:24576
	ds_read_b128 v[182:185], v230 offset:26624
	ds_read_b128 v[186:189], v230 offset:28672
	ds_read_b128 v[190:193], v230 offset:30720
	s_setprio 1
	v_mfma_f32_32x32x16_bf16 v[48:63], v[222:225], v[206:209], v[48:63]
	v_mfma_f32_32x32x16_bf16 v[32:47], v[222:225], v[210:213], v[32:47]
	v_mfma_f32_32x32x16_bf16 v[16:31], v[226:229], v[206:209], v[16:31]
	v_mfma_f32_32x32x16_bf16 v[0:15], v[226:229], v[210:213], v[0:15]
	s_setprio 0
	s_add_u32 m0, s101, 0xc000
	s_nop 0
	global_load_lds_dwordx4 v234, s[98:99]
	s_add_u32 m0, s101, 0x0
	s_nop 0
	global_load_lds_dwordx4 v234, s[44:45]
	s_add_u32 m0, s101, 0xc400
	s_nop 0
	global_load_lds_dwordx4 v235, s[98:99]
	s_add_u32 m0, s101, 0x400
	s_nop 0
	global_load_lds_dwordx4 v235, s[44:45]
	s_waitcnt lgkmcnt(2)
	s_setprio 1
	v_mfma_f32_32x32x16_bf16 v[112:127], v[178:181], v[170:173], v[112:127]
	v_mfma_f32_32x32x16_bf16 v[96:111], v[178:181], v[174:177], v[96:111]
	v_mfma_f32_32x32x16_bf16 v[80:95], v[182:185], v[170:173], v[80:95]
	v_mfma_f32_32x32x16_bf16 v[64:79], v[182:185], v[174:177], v[64:79]
	s_setprio 0
	ds_read_b128 v[206:209], v233 offset:24576
	ds_read_b128 v[210:213], v233 offset:26624
	ds_read_b128 v[214:217], v231 offset:24576
	ds_read_b128 v[218:221], v231 offset:26624
	s_add_u32 m0, s101, 0xc800
	s_nop 0
	global_load_lds_dwordx4 v236, s[98:99]
	s_add_u32 m0, s101, 0x800
	s_nop 0
	global_load_lds_dwordx4 v236, s[44:45]
	s_add_u32 m0, s101, 0xcc00
	s_nop 0
	global_load_lds_dwordx4 v237, s[98:99]
	s_add_u32 m0, s101, 0xc00
	s_nop 0
	global_load_lds_dwordx4 v237, s[44:45]
	s_waitcnt lgkmcnt(4)
	s_setprio 1
	v_mfma_f32_32x32x16_bf16 v[48:63], v[186:189], v[170:173], v[48:63]
	v_mfma_f32_32x32x16_bf16 v[32:47], v[186:189], v[174:177], v[32:47]
	v_mfma_f32_32x32x16_bf16 v[16:31], v[190:193], v[170:173], v[16:31]
	v_mfma_f32_32x32x16_bf16 v[0:15], v[190:193], v[174:177], v[0:15]
	s_setprio 0
	ds_read_b128 v[222:225], v231 offset:28672
	ds_read_b128 v[226:229], v231 offset:30720
	v_xad_u32 v241, s36, v240, v238
	v_xad_u32 v242, s37, v240, v239
	s_add_u32 m0, s49, 0xc000
	s_nop 0
	global_load_lds_dwordx4 v241, s[94:95]
	s_add_u32 m0, s49, 0xffffffc0
	s_nop 0
	global_load_lds_dwordx4 v241, s[94:95] offset:64
	s_add_u32 m0, s49, 0xc400
	s_nop 0
	global_load_lds_dwordx4 v242, s[94:95]
	s_add_u32 m0, s49, 0x3c0
	s_nop 0
	global_load_lds_dwordx4 v242, s[94:95] offset:64
	s_add_u32 s36, s36, 0x80
	s_xor_b32 s37, s36, 0x800
	s_add_u32 s98, s98, 128
	s_addc_u32 s99, s99, 0
	s_add_u32 s44, s44, 128
	s_addc_u32 s45, s45, 0
	s_waitcnt lgkmcnt(2)
	s_setprio 1
	v_mfma_f32_32x32x16_bf16 v[112:127], v[214:217], v[206:209], v[112:127]
	v_mfma_f32_32x32x16_bf16 v[96:111], v[214:217], v[210:213], v[96:111]
	v_mfma_f32_32x32x16_bf16 v[80:95], v[218:221], v[206:209], v[80:95]
	v_mfma_f32_32x32x16_bf16 v[64:79], v[218:221], v[210:213], v[64:79]
	s_setprio 0
	s_waitcnt vmcnt(0) lgkmcnt(0)
	s_barrier
	ds_read_b128 v[170:173], v232 offset:49152
	ds_read_b128 v[174:177], v232 offset:51200
	ds_read_b128 v[178:181], v230 offset:49152
	ds_read_b128 v[182:185], v230 offset:51200
	ds_read_b128 v[186:189], v230 offset:53248
	ds_read_b128 v[190:193], v230 offset:55296
	s_setprio 1
	v_mfma_f32_32x32x16_bf16 v[48:63], v[222:225], v[206:209], v[48:63]
	v_mfma_f32_32x32x16_bf16 v[32:47], v[222:225], v[210:213], v[32:47]
	v_mfma_f32_32x32x16_bf16 v[16:31], v[226:229], v[206:209], v[16:31]
	v_mfma_f32_32x32x16_bf16 v[0:15], v[226:229], v[210:213], v[0:15]
	s_setprio 0
	s_waitcnt lgkmcnt(2)
	s_setprio 1
	v_mfma_f32_32x32x16_bf16 v[112:127], v[178:181], v[170:173], v[112:127]
	v_mfma_f32_32x32x16_bf16 v[96:111], v[178:181], v[174:177], v[96:111]
	v_mfma_f32_32x32x16_bf16 v[80:95], v[182:185], v[170:173], v[80:95]
	v_mfma_f32_32x32x16_bf16 v[64:79], v[182:185], v[174:177], v[64:79]
	s_setprio 0
	ds_read_b128 v[206:209], v233 offset:49152
	ds_read_b128 v[210:213], v233 offset:51200
	ds_read_b128 v[214:217], v231 offset:49152
	ds_read_b128 v[218:221], v231 offset:51200
	s_waitcnt lgkmcnt(4)
	s_setprio 1
	v_mfma_f32_32x32x16_bf16 v[48:63], v[186:189], v[170:173], v[48:63]
	v_mfma_f32_32x32x16_bf16 v[32:47], v[186:189], v[174:177], v[32:47]
	v_mfma_f32_32x32x16_bf16 v[16:31], v[190:193], v[170:173], v[16:31]
	v_mfma_f32_32x32x16_bf16 v[0:15], v[190:193], v[174:177], v[0:15]
	s_setprio 0
	ds_read_b128 v[222:225], v231 offset:53248
	ds_read_b128 v[226:229], v231 offset:55296
	s_waitcnt lgkmcnt(2)
	s_setprio 1
	v_mfma_f32_32x32x16_bf16 v[112:127], v[214:217], v[206:209], v[112:127]
	v_mfma_f32_32x32x16_bf16 v[96:111], v[214:217], v[210:213], v[96:111]
	v_mfma_f32_32x32x16_bf16 v[80:95], v[218:221], v[206:209], v[80:95]
	v_mfma_f32_32x32x16_bf16 v[64:79], v[218:221], v[210:213], v[64:79]
	s_setprio 0
	s_waitcnt vmcnt(0) lgkmcnt(0)
	s_barrier
	ds_read_b128 v[170:173], v232 offset:0
	ds_read_b128 v[174:177], v232 offset:2048
	ds_read_b128 v[178:181], v230 offset:0
	ds_read_b128 v[182:185], v230 offset:2048
	ds_read_b128 v[186:189], v230 offset:4096
	ds_read_b128 v[190:193], v230 offset:6144
	s_setprio 1
	v_mfma_f32_32x32x16_bf16 v[48:63], v[222:225], v[206:209], v[48:63]
	v_mfma_f32_32x32x16_bf16 v[32:47], v[222:225], v[210:213], v[32:47]
	v_mfma_f32_32x32x16_bf16 v[16:31], v[226:229], v[206:209], v[16:31]
	v_mfma_f32_32x32x16_bf16 v[0:15], v[226:229], v[210:213], v[0:15]
	s_setprio 0
	s_waitcnt lgkmcnt(2)
	s_setprio 1
	v_mfma_f32_32x32x16_bf16 v[112:127], v[178:181], v[170:173], v[112:127]
	v_mfma_f32_32x32x16_bf16 v[96:111], v[178:181], v[174:177], v[96:111]
	v_mfma_f32_32x32x16_bf16 v[80:95], v[182:185], v[170:173], v[80:95]
	v_mfma_f32_32x32x16_bf16 v[64:79], v[182:185], v[174:177], v[64:79]
	s_setprio 0
	ds_read_b128 v[206:209], v233 offset:0
	ds_read_b128 v[210:213], v233 offset:2048
	ds_read_b128 v[214:217], v231 offset:0
	ds_read_b128 v[218:221], v231 offset:2048
	s_waitcnt lgkmcnt(4)
	s_setprio 1
	v_mfma_f32_32x32x16_bf16 v[48:63], v[186:189], v[170:173], v[48:63]
	v_mfma_f32_32x32x16_bf16 v[32:47], v[186:189], v[174:177], v[32:47]
	v_mfma_f32_32x32x16_bf16 v[16:31], v[190:193], v[170:173], v[16:31]
	v_mfma_f32_32x32x16_bf16 v[0:15], v[190:193], v[174:177], v[0:15]
	s_setprio 0
	ds_read_b128 v[222:225], v231 offset:4096
	ds_read_b128 v[226:229], v231 offset:6144
	s_waitcnt lgkmcnt(2)
	s_setprio 1
	v_mfma_f32_32x32x16_bf16 v[112:127], v[214:217], v[206:209], v[112:127]
	v_mfma_f32_32x32x16_bf16 v[96:111], v[214:217], v[210:213], v[96:111]
	v_mfma_f32_32x32x16_bf16 v[80:95], v[218:221], v[206:209], v[80:95]
	v_mfma_f32_32x32x16_bf16 v[64:79], v[218:221], v[210:213], v[64:79]
	s_setprio 0
	s_waitcnt lgkmcnt(0)
	s_setprio 1
	v_mfma_f32_32x32x16_bf16 v[48:63], v[222:225], v[206:209], v[48:63]
	v_mfma_f32_32x32x16_bf16 v[32:47], v[222:225], v[210:213], v[32:47]
	v_mfma_f32_32x32x16_bf16 v[16:31], v[226:229], v[206:209], v[16:31]
	v_mfma_f32_32x32x16_bf16 v[0:15], v[226:229], v[210:213], v[0:15]
	s_setprio 0
	v_mov_b32_e32 v128, v204
	s_waitcnt vmcnt(0)
	s_barrier
	s_add_u32 s46, s29, s46
	v_and_b32_e32 v129, 0x3fff80, v128
	v_lshrrev_b32_e32 v130, 3, v128
	v_and_or_b32 v129, v130, 4, v129
	s_addc_u32 s47, s30, s47
	s_lshl_b32 s33, s33, 9
	v_and_b32_e32 v128, 0x5f, v128
	v_lshlrev_b32_e32 v129, 10, v129
	s_add_u32 s46, s46, s33
	v_or_b32_e32 v130, v129, v128
	s_addc_u32 s47, s47, 0
	v_ashrrev_i32_e32 v131, 31, v130
	v_lshl_add_u64 v[132:133], v[130:131], 2, s[46:47]
	v_or_b32_e32 v134, 0x400, v129
	global_store_dword v[132:133], v112, off
	v_or_b32_e32 v132, v134, v128
	v_ashrrev_i32_e32 v133, 31, v132
	v_lshl_add_u64 v[132:133], v[132:133], 2, s[46:47]
	global_store_dword v[132:133], v113, off
	v_or_b32_e32 v132, 0x800, v129
	v_or_b32_e32 v112, v132, v128
	v_ashrrev_i32_e32 v113, 31, v112
	v_lshl_add_u64 v[112:113], v[112:113], 2, s[46:47]
	v_or_b32_e32 v133, 0xc00, v129
	global_store_dword v[112:113], v114, off
	v_or_b32_e32 v112, v133, v128
	v_ashrrev_i32_e32 v113, 31, v112
	v_lshl_add_u64 v[112:113], v[112:113], 2, s[46:47]
	v_or_b32_e32 v135, 0x2000, v129
	global_store_dword v[112:113], v115, off
	v_or_b32_e32 v112, v135, v128
	v_ashrrev_i32_e32 v113, 31, v112
	v_lshl_add_u64 v[112:113], v[112:113], 2, s[46:47]
	global_store_dword v[112:113], v116, off
	v_or_b32_e32 v116, 0x2400, v129
	v_or_b32_e32 v112, v116, v128
	v_ashrrev_i32_e32 v113, 31, v112
	v_lshl_add_u64 v[112:113], v[112:113], 2, s[46:47]
	global_store_dword v[112:113], v117, off
	v_or_b32_e32 v117, 0x2800, v129
	v_or_b32_e32 v112, v117, v128
	v_ashrrev_i32_e32 v113, 31, v112
	v_lshl_add_u64 v[112:113], v[112:113], 2, s[46:47]
	global_store_dword v[112:113], v118, off
	v_or_b32_e32 v118, 0x2c00, v129
	v_or_b32_e32 v112, v118, v128
	v_ashrrev_i32_e32 v113, 31, v112
	v_lshl_add_u64 v[112:113], v[112:113], 2, s[46:47]
	global_store_dword v[112:113], v119, off
	v_or_b32_e32 v119, 0x4000, v129
	v_or_b32_e32 v112, v119, v128
	v_ashrrev_i32_e32 v113, 31, v112
	v_lshl_add_u64 v[112:113], v[112:113], 2, s[46:47]
	global_store_dword v[112:113], v120, off
	v_or_b32_e32 v120, 0x4400, v129
	v_or_b32_e32 v112, v120, v128
	v_ashrrev_i32_e32 v113, 31, v112
	v_lshl_add_u64 v[112:113], v[112:113], 2, s[46:47]
	global_store_dword v[112:113], v121, off
	v_or_b32_e32 v121, 0x4800, v129
	v_or_b32_e32 v112, v121, v128
	v_ashrrev_i32_e32 v113, 31, v112
	v_lshl_add_u64 v[112:113], v[112:113], 2, s[46:47]
	global_store_dword v[112:113], v122, off
	v_or_b32_e32 v122, 0x4c00, v129
	v_or_b32_e32 v112, v122, v128
	v_ashrrev_i32_e32 v113, 31, v112
	v_lshl_add_u64 v[112:113], v[112:113], 2, s[46:47]
	global_store_dword v[112:113], v123, off
	v_or_b32_e32 v123, 0x6000, v129
	v_or_b32_e32 v112, v123, v128
	v_ashrrev_i32_e32 v113, 31, v112
	v_lshl_add_u64 v[112:113], v[112:113], 2, s[46:47]
	global_store_dword v[112:113], v124, off
	v_or_b32_e32 v124, 0x6400, v129
	v_or_b32_e32 v112, v124, v128
	v_ashrrev_i32_e32 v113, 31, v112
	v_lshl_add_u64 v[112:113], v[112:113], 2, s[46:47]
	global_store_dword v[112:113], v125, off
	v_or_b32_e32 v125, 0x6800, v129
	v_or_b32_e32 v112, v125, v128
	v_ashrrev_i32_e32 v113, 31, v112
	v_lshl_add_u64 v[112:113], v[112:113], 2, s[46:47]
	global_store_dword v[112:113], v126, off
	v_or_b32_e32 v126, 0x6c00, v129
	v_or_b32_e32 v112, v126, v128
	v_ashrrev_i32_e32 v113, 31, v112
	v_lshl_add_u64 v[112:113], v[112:113], 2, s[46:47]
	v_ashrrev_i32_e32 v131, 31, v129
	global_store_dword v[112:113], v127, off
	v_or_b32_e32 v112, 32, v128
	v_lshl_add_u64 v[114:115], v[130:131], 2, s[46:47]
	global_store_dword v[114:115], v96, off offset:128
	v_or_b32_e32 v114, v134, v112
	v_ashrrev_i32_e32 v115, 31, v114
	v_lshl_add_u64 v[114:115], v[114:115], 2, s[46:47]
	v_or_b32_e32 v96, v132, v112
	global_store_dword v[114:115], v97, off
	v_ashrrev_i32_e32 v97, 31, v96
	v_lshl_add_u64 v[96:97], v[96:97], 2, s[46:47]
	global_store_dword v[96:97], v98, off
	v_or_b32_e32 v96, v133, v112
	v_ashrrev_i32_e32 v97, 31, v96
	v_lshl_add_u64 v[96:97], v[96:97], 2, s[46:47]
	global_store_dword v[96:97], v99, off
	v_or_b32_e32 v96, v135, v112
	v_ashrrev_i32_e32 v97, 31, v96
	v_lshl_add_u64 v[96:97], v[96:97], 2, s[46:47]
	global_store_dword v[96:97], v100, off
	v_or_b32_e32 v96, v116, v112
	v_ashrrev_i32_e32 v97, 31, v96
	v_lshl_add_u64 v[96:97], v[96:97], 2, s[46:47]
	global_store_dword v[96:97], v101, off
	v_or_b32_e32 v96, v117, v112
	v_ashrrev_i32_e32 v97, 31, v96
	v_lshl_add_u64 v[96:97], v[96:97], 2, s[46:47]
	global_store_dword v[96:97], v102, off
	v_or_b32_e32 v96, v118, v112
	v_ashrrev_i32_e32 v97, 31, v96
	v_lshl_add_u64 v[96:97], v[96:97], 2, s[46:47]
	global_store_dword v[96:97], v103, off
	v_or_b32_e32 v96, v119, v112
	v_ashrrev_i32_e32 v97, 31, v96
	v_lshl_add_u64 v[96:97], v[96:97], 2, s[46:47]
	global_store_dword v[96:97], v104, off
	v_or_b32_e32 v96, v120, v112
	v_ashrrev_i32_e32 v97, 31, v96
	v_lshl_add_u64 v[96:97], v[96:97], 2, s[46:47]
	global_store_dword v[96:97], v105, off
	v_or_b32_e32 v96, v121, v112
	v_ashrrev_i32_e32 v97, 31, v96
	v_lshl_add_u64 v[96:97], v[96:97], 2, s[46:47]
	global_store_dword v[96:97], v106, off
	v_or_b32_e32 v96, v122, v112
	v_ashrrev_i32_e32 v97, 31, v96
	v_lshl_add_u64 v[96:97], v[96:97], 2, s[46:47]
	global_store_dword v[96:97], v107, off
	v_or_b32_e32 v96, v123, v112
	v_ashrrev_i32_e32 v97, 31, v96
	v_lshl_add_u64 v[96:97], v[96:97], 2, s[46:47]
	global_store_dword v[96:97], v108, off
	v_or_b32_e32 v96, v124, v112
	v_ashrrev_i32_e32 v97, 31, v96
	v_lshl_add_u64 v[96:97], v[96:97], 2, s[46:47]
	global_store_dword v[96:97], v109, off
	v_or_b32_e32 v96, v125, v112
	v_ashrrev_i32_e32 v97, 31, v96
	v_lshl_add_u64 v[96:97], v[96:97], 2, s[46:47]
	global_store_dword v[96:97], v110, off
	v_or_b32_e32 v96, v126, v112
	v_ashrrev_i32_e32 v97, 31, v96
	v_lshl_add_u64 v[96:97], v[96:97], 2, s[46:47]
	v_or_b32_e32 v98, 0x8000, v129
	global_store_dword v[96:97], v111, off
	v_or_b32_e32 v96, v98, v128
	v_ashrrev_i32_e32 v97, 31, v96
	v_lshl_add_u64 v[96:97], v[96:97], 2, s[46:47]
	v_or_b32_e32 v99, 0x8400, v129
	global_store_dword v[96:97], v80, off
	v_or_b32_e32 v96, v99, v128
	v_ashrrev_i32_e32 v97, 31, v96
	v_lshl_add_u64 v[96:97], v[96:97], 2, s[46:47]
	global_store_dword v[96:97], v81, off
	v_or_b32_e32 v96, 0x8800, v129
	v_or_b32_e32 v80, v96, v128
	v_ashrrev_i32_e32 v81, 31, v80
	v_lshl_add_u64 v[80:81], v[80:81], 2, s[46:47]
	global_store_dword v[80:81], v82, off
	v_or_b32_e32 v82, 0x8c00, v129
	v_or_b32_e32 v80, v82, v128
	v_ashrrev_i32_e32 v81, 31, v80
	v_lshl_add_u64 v[80:81], v[80:81], 2, s[46:47]
	global_store_dword v[80:81], v83, off
	v_or_b32_e32 v83, 0xa000, v129
	v_or_b32_e32 v80, v83, v128
	v_ashrrev_i32_e32 v81, 31, v80
	v_lshl_add_u64 v[80:81], v[80:81], 2, s[46:47]
	global_store_dword v[80:81], v84, off
	v_or_b32_e32 v84, 0xa400, v129
	v_or_b32_e32 v80, v84, v128
	v_ashrrev_i32_e32 v81, 31, v80
	v_lshl_add_u64 v[80:81], v[80:81], 2, s[46:47]
	global_store_dword v[80:81], v85, off
	v_or_b32_e32 v85, 0xa800, v129
	v_or_b32_e32 v80, v85, v128
	v_ashrrev_i32_e32 v81, 31, v80
	v_lshl_add_u64 v[80:81], v[80:81], 2, s[46:47]
	global_store_dword v[80:81], v86, off
	v_or_b32_e32 v86, 0xac00, v129
	v_or_b32_e32 v80, v86, v128
	v_ashrrev_i32_e32 v81, 31, v80
	v_lshl_add_u64 v[80:81], v[80:81], 2, s[46:47]
	global_store_dword v[80:81], v87, off
	v_or_b32_e32 v87, 0xc000, v129
	v_or_b32_e32 v80, v87, v128
	v_ashrrev_i32_e32 v81, 31, v80
	v_lshl_add_u64 v[80:81], v[80:81], 2, s[46:47]
	global_store_dword v[80:81], v88, off
	v_or_b32_e32 v88, 0xc400, v129
	v_or_b32_e32 v80, v88, v128
	v_ashrrev_i32_e32 v81, 31, v80
	v_lshl_add_u64 v[80:81], v[80:81], 2, s[46:47]
	global_store_dword v[80:81], v89, off
	v_or_b32_e32 v89, 0xc800, v129
	v_or_b32_e32 v80, v89, v128
	v_ashrrev_i32_e32 v81, 31, v80
	v_lshl_add_u64 v[80:81], v[80:81], 2, s[46:47]
	global_store_dword v[80:81], v90, off
	v_or_b32_e32 v90, 0xcc00, v129
	v_or_b32_e32 v80, v90, v128
	v_ashrrev_i32_e32 v81, 31, v80
	v_lshl_add_u64 v[80:81], v[80:81], 2, s[46:47]
	global_store_dword v[80:81], v91, off
	v_or_b32_e32 v91, 0xe000, v129
	v_or_b32_e32 v80, v91, v128
	v_ashrrev_i32_e32 v81, 31, v80
	v_lshl_add_u64 v[80:81], v[80:81], 2, s[46:47]
	global_store_dword v[80:81], v92, off
	v_or_b32_e32 v92, 0xe400, v129
	v_or_b32_e32 v80, v92, v128
	v_ashrrev_i32_e32 v81, 31, v80
	v_lshl_add_u64 v[80:81], v[80:81], 2, s[46:47]
	global_store_dword v[80:81], v93, off
	v_or_b32_e32 v93, 0xe800, v129
	v_or_b32_e32 v80, v93, v128
	v_ashrrev_i32_e32 v81, 31, v80
	v_lshl_add_u64 v[80:81], v[80:81], 2, s[46:47]
	global_store_dword v[80:81], v94, off
	v_or_b32_e32 v94, 0xec00, v129
	v_or_b32_e32 v80, v94, v128
	v_ashrrev_i32_e32 v81, 31, v80
	v_lshl_add_u64 v[80:81], v[80:81], 2, s[46:47]
	global_store_dword v[80:81], v95, off
	v_or_b32_e32 v80, v98, v112
	v_ashrrev_i32_e32 v81, 31, v80
	v_lshl_add_u64 v[80:81], v[80:81], 2, s[46:47]
	global_store_dword v[80:81], v64, off
	v_or_b32_e32 v80, v99, v112
	v_ashrrev_i32_e32 v81, 31, v80
	v_lshl_add_u64 v[80:81], v[80:81], 2, s[46:47]
	v_or_b32_e32 v64, v96, v112
	global_store_dword v[80:81], v65, off
	v_ashrrev_i32_e32 v65, 31, v64
	v_lshl_add_u64 v[64:65], v[64:65], 2, s[46:47]
	global_store_dword v[64:65], v66, off
	v_or_b32_e32 v64, v82, v112
	v_ashrrev_i32_e32 v65, 31, v64
	v_lshl_add_u64 v[64:65], v[64:65], 2, s[46:47]
	global_store_dword v[64:65], v67, off
	v_or_b32_e32 v64, v83, v112
	v_ashrrev_i32_e32 v65, 31, v64
	v_lshl_add_u64 v[64:65], v[64:65], 2, s[46:47]
	global_store_dword v[64:65], v68, off
	v_or_b32_e32 v64, v84, v112
	v_ashrrev_i32_e32 v65, 31, v64
	v_lshl_add_u64 v[64:65], v[64:65], 2, s[46:47]
	global_store_dword v[64:65], v69, off
	v_or_b32_e32 v64, v85, v112
	v_ashrrev_i32_e32 v65, 31, v64
	v_lshl_add_u64 v[64:65], v[64:65], 2, s[46:47]
	global_store_dword v[64:65], v70, off
	v_or_b32_e32 v64, v86, v112
	v_ashrrev_i32_e32 v65, 31, v64
	v_lshl_add_u64 v[64:65], v[64:65], 2, s[46:47]
	global_store_dword v[64:65], v71, off
	v_or_b32_e32 v64, v87, v112
	v_ashrrev_i32_e32 v65, 31, v64
	v_lshl_add_u64 v[64:65], v[64:65], 2, s[46:47]
	global_store_dword v[64:65], v72, off
	v_or_b32_e32 v64, v88, v112
	v_ashrrev_i32_e32 v65, 31, v64
	v_lshl_add_u64 v[64:65], v[64:65], 2, s[46:47]
	global_store_dword v[64:65], v73, off
	v_or_b32_e32 v64, v89, v112
	v_ashrrev_i32_e32 v65, 31, v64
	v_lshl_add_u64 v[64:65], v[64:65], 2, s[46:47]
	global_store_dword v[64:65], v74, off
	v_or_b32_e32 v64, v90, v112
	v_ashrrev_i32_e32 v65, 31, v64
	v_lshl_add_u64 v[64:65], v[64:65], 2, s[46:47]
	global_store_dword v[64:65], v75, off
	v_or_b32_e32 v64, v91, v112
	v_ashrrev_i32_e32 v65, 31, v64
	v_lshl_add_u64 v[64:65], v[64:65], 2, s[46:47]
	global_store_dword v[64:65], v76, off
	v_or_b32_e32 v64, v92, v112
	v_ashrrev_i32_e32 v65, 31, v64
	v_lshl_add_u64 v[64:65], v[64:65], 2, s[46:47]
	global_store_dword v[64:65], v77, off
	v_or_b32_e32 v64, v93, v112
	v_ashrrev_i32_e32 v65, 31, v64
	v_lshl_add_u64 v[64:65], v[64:65], 2, s[46:47]
	global_store_dword v[64:65], v78, off
	v_or_b32_e32 v64, v94, v112
	v_ashrrev_i32_e32 v65, 31, v64
	v_lshl_add_u64 v[64:65], v[64:65], 2, s[46:47]
	v_or_b32_e32 v66, 0x10000, v129
	global_store_dword v[64:65], v79, off
	v_or_b32_e32 v64, v66, v128
	v_ashrrev_i32_e32 v65, 31, v64
	v_lshl_add_u64 v[64:65], v[64:65], 2, s[46:47]
	v_or_b32_e32 v67, 0x10400, v129
	global_store_dword v[64:65], v48, off
	v_or_b32_e32 v64, v67, v128
	v_ashrrev_i32_e32 v65, 31, v64
	v_lshl_add_u64 v[64:65], v[64:65], 2, s[46:47]
	global_store_dword v[64:65], v49, off
	v_or_b32_e32 v64, 0x10800, v129
	v_or_b32_e32 v48, v64, v128
	v_ashrrev_i32_e32 v49, 31, v48
	v_lshl_add_u64 v[48:49], v[48:49], 2, s[46:47]
	global_store_dword v[48:49], v50, off
	v_or_b32_e32 v50, 0x10c00, v129
	v_or_b32_e32 v48, v50, v128
	v_ashrrev_i32_e32 v49, 31, v48
	v_lshl_add_u64 v[48:49], v[48:49], 2, s[46:47]
	global_store_dword v[48:49], v51, off
	v_or_b32_e32 v51, 0x12000, v129
	v_or_b32_e32 v48, v51, v128
	v_ashrrev_i32_e32 v49, 31, v48
	v_lshl_add_u64 v[48:49], v[48:49], 2, s[46:47]
	global_store_dword v[48:49], v52, off
	v_or_b32_e32 v52, 0x12400, v129
	v_or_b32_e32 v48, v52, v128
	v_ashrrev_i32_e32 v49, 31, v48
	v_lshl_add_u64 v[48:49], v[48:49], 2, s[46:47]
	global_store_dword v[48:49], v53, off
	v_or_b32_e32 v53, 0x12800, v129
	v_or_b32_e32 v48, v53, v128
	v_ashrrev_i32_e32 v49, 31, v48
	v_lshl_add_u64 v[48:49], v[48:49], 2, s[46:47]
	global_store_dword v[48:49], v54, off
	v_or_b32_e32 v54, 0x12c00, v129
	v_or_b32_e32 v48, v54, v128
	v_ashrrev_i32_e32 v49, 31, v48
	v_lshl_add_u64 v[48:49], v[48:49], 2, s[46:47]
	global_store_dword v[48:49], v55, off
	v_or_b32_e32 v55, 0x14000, v129
	v_or_b32_e32 v48, v55, v128
	v_ashrrev_i32_e32 v49, 31, v48
	v_lshl_add_u64 v[48:49], v[48:49], 2, s[46:47]
	global_store_dword v[48:49], v56, off
	v_or_b32_e32 v56, 0x14400, v129
	v_or_b32_e32 v48, v56, v128
	v_ashrrev_i32_e32 v49, 31, v48
	v_lshl_add_u64 v[48:49], v[48:49], 2, s[46:47]
	global_store_dword v[48:49], v57, off
	v_or_b32_e32 v57, 0x14800, v129
	v_or_b32_e32 v48, v57, v128
	v_ashrrev_i32_e32 v49, 31, v48
	v_lshl_add_u64 v[48:49], v[48:49], 2, s[46:47]
	global_store_dword v[48:49], v58, off
	v_or_b32_e32 v58, 0x14c00, v129
	v_or_b32_e32 v48, v58, v128
	v_ashrrev_i32_e32 v49, 31, v48
	v_lshl_add_u64 v[48:49], v[48:49], 2, s[46:47]
	global_store_dword v[48:49], v59, off
	v_or_b32_e32 v59, 0x16000, v129
	v_or_b32_e32 v48, v59, v128
	v_ashrrev_i32_e32 v49, 31, v48
	v_lshl_add_u64 v[48:49], v[48:49], 2, s[46:47]
	global_store_dword v[48:49], v60, off
	v_or_b32_e32 v60, 0x16400, v129
	v_or_b32_e32 v48, v60, v128
	v_ashrrev_i32_e32 v49, 31, v48
	v_lshl_add_u64 v[48:49], v[48:49], 2, s[46:47]
	global_store_dword v[48:49], v61, off
	v_or_b32_e32 v61, 0x16800, v129
	v_or_b32_e32 v48, v61, v128
	v_ashrrev_i32_e32 v49, 31, v48
	v_lshl_add_u64 v[48:49], v[48:49], 2, s[46:47]
	global_store_dword v[48:49], v62, off
	v_or_b32_e32 v62, 0x16c00, v129
	v_or_b32_e32 v48, v62, v128
	v_ashrrev_i32_e32 v49, 31, v48
	v_lshl_add_u64 v[48:49], v[48:49], 2, s[46:47]
	global_store_dword v[48:49], v63, off
	v_or_b32_e32 v48, v66, v112
	v_ashrrev_i32_e32 v49, 31, v48
	v_lshl_add_u64 v[48:49], v[48:49], 2, s[46:47]
	global_store_dword v[48:49], v32, off
	v_or_b32_e32 v48, v67, v112
	v_ashrrev_i32_e32 v49, 31, v48
	v_lshl_add_u64 v[48:49], v[48:49], 2, s[46:47]
	v_or_b32_e32 v32, v64, v112
	global_store_dword v[48:49], v33, off
	v_ashrrev_i32_e32 v33, 31, v32
	v_lshl_add_u64 v[32:33], v[32:33], 2, s[46:47]
	global_store_dword v[32:33], v34, off
	v_or_b32_e32 v32, v50, v112
	v_ashrrev_i32_e32 v33, 31, v32
	v_lshl_add_u64 v[32:33], v[32:33], 2, s[46:47]
	global_store_dword v[32:33], v35, off
	v_or_b32_e32 v32, v51, v112
	v_ashrrev_i32_e32 v33, 31, v32
	v_lshl_add_u64 v[32:33], v[32:33], 2, s[46:47]
	global_store_dword v[32:33], v36, off
	v_or_b32_e32 v32, v52, v112
	v_ashrrev_i32_e32 v33, 31, v32
	v_lshl_add_u64 v[32:33], v[32:33], 2, s[46:47]
	global_store_dword v[32:33], v37, off
	v_or_b32_e32 v32, v53, v112
	v_ashrrev_i32_e32 v33, 31, v32
	v_lshl_add_u64 v[32:33], v[32:33], 2, s[46:47]
	global_store_dword v[32:33], v38, off
	v_or_b32_e32 v32, v54, v112
	v_ashrrev_i32_e32 v33, 31, v32
	v_lshl_add_u64 v[32:33], v[32:33], 2, s[46:47]
	global_store_dword v[32:33], v39, off
	v_or_b32_e32 v32, v55, v112
	v_ashrrev_i32_e32 v33, 31, v32
	v_lshl_add_u64 v[32:33], v[32:33], 2, s[46:47]
	global_store_dword v[32:33], v40, off
	v_or_b32_e32 v32, v56, v112
	v_ashrrev_i32_e32 v33, 31, v32
	v_lshl_add_u64 v[32:33], v[32:33], 2, s[46:47]
	global_store_dword v[32:33], v41, off
	v_or_b32_e32 v32, v57, v112
	v_ashrrev_i32_e32 v33, 31, v32
	v_lshl_add_u64 v[32:33], v[32:33], 2, s[46:47]
	global_store_dword v[32:33], v42, off
	v_or_b32_e32 v32, v58, v112
	v_ashrrev_i32_e32 v33, 31, v32
	v_lshl_add_u64 v[32:33], v[32:33], 2, s[46:47]
	global_store_dword v[32:33], v43, off
	v_or_b32_e32 v32, v59, v112
	v_ashrrev_i32_e32 v33, 31, v32
	v_lshl_add_u64 v[32:33], v[32:33], 2, s[46:47]
	global_store_dword v[32:33], v44, off
	v_or_b32_e32 v32, v60, v112
	v_ashrrev_i32_e32 v33, 31, v32
	v_lshl_add_u64 v[32:33], v[32:33], 2, s[46:47]
	global_store_dword v[32:33], v45, off
	v_or_b32_e32 v32, v61, v112
	v_ashrrev_i32_e32 v33, 31, v32
	v_lshl_add_u64 v[32:33], v[32:33], 2, s[46:47]
	global_store_dword v[32:33], v46, off
	v_or_b32_e32 v32, v62, v112
	v_ashrrev_i32_e32 v33, 31, v32
	v_lshl_add_u64 v[32:33], v[32:33], 2, s[46:47]
	v_or_b32_e32 v34, 0x18000, v129
	global_store_dword v[32:33], v47, off
	v_or_b32_e32 v32, v34, v128
	v_ashrrev_i32_e32 v33, 31, v32
	v_lshl_add_u64 v[32:33], v[32:33], 2, s[46:47]
	v_or_b32_e32 v35, 0x18400, v129
	global_store_dword v[32:33], v16, off
	v_or_b32_e32 v32, v35, v128
	v_ashrrev_i32_e32 v33, 31, v32
	v_lshl_add_u64 v[32:33], v[32:33], 2, s[46:47]
	global_store_dword v[32:33], v17, off
	v_or_b32_e32 v32, 0x18800, v129
	v_or_b32_e32 v16, v32, v128
	v_ashrrev_i32_e32 v17, 31, v16
	v_lshl_add_u64 v[16:17], v[16:17], 2, s[46:47]
	global_store_dword v[16:17], v18, off
	v_or_b32_e32 v18, 0x18c00, v129
	v_or_b32_e32 v16, v18, v128
	v_ashrrev_i32_e32 v17, 31, v16
	v_lshl_add_u64 v[16:17], v[16:17], 2, s[46:47]
	global_store_dword v[16:17], v19, off
	v_or_b32_e32 v19, 0x1a000, v129
	v_or_b32_e32 v16, v19, v128
	v_ashrrev_i32_e32 v17, 31, v16
	v_lshl_add_u64 v[16:17], v[16:17], 2, s[46:47]
	global_store_dword v[16:17], v20, off
	v_or_b32_e32 v20, 0x1a400, v129
	v_or_b32_e32 v16, v20, v128
	v_ashrrev_i32_e32 v17, 31, v16
	v_lshl_add_u64 v[16:17], v[16:17], 2, s[46:47]
	global_store_dword v[16:17], v21, off
	v_or_b32_e32 v21, 0x1a800, v129
	v_or_b32_e32 v16, v21, v128
	v_ashrrev_i32_e32 v17, 31, v16
	v_lshl_add_u64 v[16:17], v[16:17], 2, s[46:47]
	global_store_dword v[16:17], v22, off
	v_or_b32_e32 v22, 0x1ac00, v129
	v_or_b32_e32 v16, v22, v128
	v_ashrrev_i32_e32 v17, 31, v16
	v_lshl_add_u64 v[16:17], v[16:17], 2, s[46:47]
	global_store_dword v[16:17], v23, off
	v_or_b32_e32 v23, 0x1c000, v129
	v_or_b32_e32 v16, v23, v128
	v_ashrrev_i32_e32 v17, 31, v16
	v_lshl_add_u64 v[16:17], v[16:17], 2, s[46:47]
	global_store_dword v[16:17], v24, off
	v_or_b32_e32 v24, 0x1c400, v129
	v_or_b32_e32 v16, v24, v128
	v_ashrrev_i32_e32 v17, 31, v16
	v_lshl_add_u64 v[16:17], v[16:17], 2, s[46:47]
	global_store_dword v[16:17], v25, off
	v_or_b32_e32 v25, 0x1c800, v129
	v_or_b32_e32 v16, v25, v128
	v_ashrrev_i32_e32 v17, 31, v16
	v_lshl_add_u64 v[16:17], v[16:17], 2, s[46:47]
	global_store_dword v[16:17], v26, off
	v_or_b32_e32 v26, 0x1cc00, v129
	v_or_b32_e32 v16, v26, v128
	v_ashrrev_i32_e32 v17, 31, v16
	v_lshl_add_u64 v[16:17], v[16:17], 2, s[46:47]
	global_store_dword v[16:17], v27, off
	v_or_b32_e32 v27, 0x1e000, v129
	v_or_b32_e32 v16, v27, v128
	v_ashrrev_i32_e32 v17, 31, v16
	v_lshl_add_u64 v[16:17], v[16:17], 2, s[46:47]
	global_store_dword v[16:17], v28, off
	v_or_b32_e32 v28, 0x1e400, v129
	v_or_b32_e32 v16, v28, v128
	v_ashrrev_i32_e32 v17, 31, v16
	v_lshl_add_u64 v[16:17], v[16:17], 2, s[46:47]
	global_store_dword v[16:17], v29, off
	v_or_b32_e32 v29, 0x1e800, v129
	v_or_b32_e32 v16, v29, v128
	v_ashrrev_i32_e32 v17, 31, v16
	v_lshl_add_u64 v[16:17], v[16:17], 2, s[46:47]
	global_store_dword v[16:17], v30, off
	v_or_b32_e32 v30, 0x1ec00, v129
	v_or_b32_e32 v16, v30, v128
	v_ashrrev_i32_e32 v17, 31, v16
	v_lshl_add_u64 v[16:17], v[16:17], 2, s[46:47]
	global_store_dword v[16:17], v31, off
	v_or_b32_e32 v16, v34, v112
	v_ashrrev_i32_e32 v17, 31, v16
	v_lshl_add_u64 v[16:17], v[16:17], 2, s[46:47]
	global_store_dword v[16:17], v0, off
	v_or_b32_e32 v16, v35, v112
	v_ashrrev_i32_e32 v17, 31, v16
	v_lshl_add_u64 v[16:17], v[16:17], 2, s[46:47]
	v_or_b32_e32 v0, v32, v112
	global_store_dword v[16:17], v1, off
	v_ashrrev_i32_e32 v1, 31, v0
	v_lshl_add_u64 v[0:1], v[0:1], 2, s[46:47]
	global_store_dword v[0:1], v2, off
	v_or_b32_e32 v0, v18, v112
	v_ashrrev_i32_e32 v1, 31, v0
	v_lshl_add_u64 v[0:1], v[0:1], 2, s[46:47]
	global_store_dword v[0:1], v3, off
	v_or_b32_e32 v0, v19, v112
	v_ashrrev_i32_e32 v1, 31, v0
	v_lshl_add_u64 v[0:1], v[0:1], 2, s[46:47]
	global_store_dword v[0:1], v4, off
	v_or_b32_e32 v0, v20, v112
	v_ashrrev_i32_e32 v1, 31, v0
	v_lshl_add_u64 v[0:1], v[0:1], 2, s[46:47]
	global_store_dword v[0:1], v5, off
	v_or_b32_e32 v0, v21, v112
	v_ashrrev_i32_e32 v1, 31, v0
	v_lshl_add_u64 v[0:1], v[0:1], 2, s[46:47]
	global_store_dword v[0:1], v6, off
	v_or_b32_e32 v0, v22, v112
	v_ashrrev_i32_e32 v1, 31, v0
	v_lshl_add_u64 v[0:1], v[0:1], 2, s[46:47]
	global_store_dword v[0:1], v7, off
	v_or_b32_e32 v0, v23, v112
	v_ashrrev_i32_e32 v1, 31, v0
	v_lshl_add_u64 v[0:1], v[0:1], 2, s[46:47]
	global_store_dword v[0:1], v8, off
	v_or_b32_e32 v0, v24, v112
	v_ashrrev_i32_e32 v1, 31, v0
	v_lshl_add_u64 v[0:1], v[0:1], 2, s[46:47]
	global_store_dword v[0:1], v9, off
	v_or_b32_e32 v0, v25, v112
	v_ashrrev_i32_e32 v1, 31, v0
	v_lshl_add_u64 v[0:1], v[0:1], 2, s[46:47]
	global_store_dword v[0:1], v10, off
	v_or_b32_e32 v0, v26, v112
	v_ashrrev_i32_e32 v1, 31, v0
	v_lshl_add_u64 v[0:1], v[0:1], 2, s[46:47]
	global_store_dword v[0:1], v11, off
	v_or_b32_e32 v0, v27, v112
	v_ashrrev_i32_e32 v1, 31, v0
	v_lshl_add_u64 v[0:1], v[0:1], 2, s[46:47]
	global_store_dword v[0:1], v12, off
	v_or_b32_e32 v0, v28, v112
	v_ashrrev_i32_e32 v1, 31, v0
	v_lshl_add_u64 v[0:1], v[0:1], 2, s[46:47]
	global_store_dword v[0:1], v13, off
	v_or_b32_e32 v0, v29, v112
	v_ashrrev_i32_e32 v1, 31, v0
	v_lshl_add_u64 v[0:1], v[0:1], 2, s[46:47]
	global_store_dword v[0:1], v14, off
	v_or_b32_e32 v0, v30, v112
	v_ashrrev_i32_e32 v1, 31, v0
	v_lshl_add_u64 v[0:1], v[0:1], 2, s[46:47]
	global_store_dword v[0:1], v15, off
	s_add_i32 s16, s16, s3
	s_add_i32 s31, s31, s3
	s_cmp_lt_i32 s16, 32
	s_cbranch_scc1 .LBB0_133
